# w_in V-columns GEMM epilogue: transposed 8-byte row-per-lane stores -> v_permlane16_swap pairs + 16-byte stores (on top of static prio build)
# speedup vs baseline: 1.0009x; 1.0009x over previous
; #define PG8_STAGE(bufoff, gbase, voff) do { _Pragma("unroll") for (int _i = 0; _i < 2; ++_i) \
;     __builtin_amdgcn_global_load_lds((const unsigned*)((const char*)(gbase) + (voff)[_i]), (PG8_LAS unsigned*)(lds + (bufoff) + ldsw + _i * 8192), 16, 0, 0); } while (0)
; #define PG8_LDA(dst, b, h) do { _Pragma("unroll") for (int m = 0; m < 4; ++m) _Pragma("unroll") for (int k = 0; k < 2; ++k) dst[m][k] = *(const PG8_LAS bf16x8*)(lds + PG8_SA(b, h) + aoff + m * 2048 + k * 1024); } while (0)
; #define PG8_LDB(dst, b, h) do { _Pragma("unroll") for (int n = 0; n < 2; ++n) _Pragma("unroll") for (int k = 0; k < 2; ++k) dst[n][k] = *(const PG8_LAS bf16x8*)(lds + PG8_SB(b, h) + boff + n * 2048 + k * 1024); } while (0)
; #define PG8_WAIT_V(n) asm volatile("s_waitcnt vmcnt(" #n ")" ::: "memory")
; template <class Epi>
; DI void gemm_phase(PG8_LAS unsigned char* lds, const Gemm g, const StaticOrder& S, const Epi& E) {
;     ...
;     for (int t = 0; t < nt; t += 2) {
;       const bool last = (t == nt - 2);
;       const char* a1 = cA + (size_t)(t + 1) * kstepA;
;       const char* a2 = last ? nA : cA + (size_t)(t + 2) * kstepA; const char* b2 = last ? nB : cB + (size_t)(t + 2) * kstep;
;       const char* a3 = a2 + kstepA; const char* b3 = b2 + kstep;
;       PG8_LDB(B0, 0, 0); PG8_SCHED; PG8_LDA(At, 0, 0); PG8_STAGE(PG8_SA(1, 1), a1 + hstepA, voffA);
;       PG8_WAIT_L(8); PG8_BAR; PG8_WAIT_L(0); PG8_MMA(0, 0, At, B0); PG8_BAR; PG8_SCHED;
;       PG8_LDB(B1, 0, 1); PG8_STAGE(PG8_SB(0, 0), b2, voffB);
;       PG8_BAR; PG8_WAIT_L(0); PG8_MMA(0, 1, At, B1); PG8_BAR;
;       PG8_LDA(At, 0, 1); PG8_STAGE(PG8_SA(0, 0), a2, voffA);
;       PG8_BAR; PG8_WAIT_L(0); PG8_MMA(1, 0, At, B0); PG8_BAR; PG8_SCHED;
;       PG8_STAGE(PG8_SB(0, 1), b2 + hstepB, voffB);
;       PG8_WAIT_V(6); PG8_BAR; PG8_MMA(1, 1, At, B1); PG8_BAR;
;       PG8_LDB(B0, 1, 0); PG8_SCHED; PG8_LDA(At, 1, 0); PG8_STAGE(PG8_SA(0, 1), a2 + hstepA, voffA);
;       PG8_WAIT_L(8); PG8_BAR; PG8_WAIT_L(0); PG8_MMA(0, 0, At, B0); PG8_BAR; PG8_SCHED;
;       PG8_LDB(B1, 1, 1); PG8_STAGE(PG8_SB(1, 0), b3, voffB);
;       PG8_BAR; PG8_WAIT_L(0); PG8_MMA(0, 1, At, B1); PG8_BAR;
;       PG8_LDA(At, 1, 1); PG8_STAGE(PG8_SA(1, 0), a3, voffA);
;       PG8_BAR; PG8_WAIT_L(0); PG8_MMA(1, 0, At, B0); PG8_BAR; PG8_SCHED;
;       PG8_STAGE(PG8_SB(1, 1), b3 + hstepB, voffB);
;       PG8_WAIT_V(6); PG8_BAR; PG8_MMA(1, 1, At, B1); PG8_BAR;
.LBB0_549:
	s_add_u32 s10, s8, 0xfffc0080
	s_addc_u32 s11, s9, -1
	s_add_i32 s55, 0, 0x10000
	v_add_u32_e32 v0, s55, v173
	s_waitcnt vmcnt(0)
	ds_read_b128 v[130:133], v0
	ds_read_b128 v[134:137], v0 offset:1024
	ds_read_b128 v[138:141], v0 offset:2048
	ds_read_b128 v[142:145], v0 offset:3072
	s_cmp_eq_u32 s54, 12
	s_cselect_b32 s29, s3, s11
	s_cselect_b32 s28, s50, s10
	s_cselect_b32 s11, s1, s53
	s_cselect_b32 s10, s51, s52
	v_lshl_add_u64 v[200:201], s[8:9], 0, v[158:159]
	s_add_i32 m0, s41, 0xc000
	ds_read_b128 v[162:165], v175
	ds_read_b128 v[168:171], v175 offset:1024
	ds_read_b128 v[176:179], v175 offset:2048
	ds_read_b128 v[180:183], v175 offset:3072
	ds_read_b128 v[184:187], v175 offset:4096
	ds_read_b128 v[188:191], v175 offset:5120
	ds_read_b128 v[192:195], v175 offset:6144
	ds_read_b128 v[196:199], v175 offset:7168
	global_load_lds_dwordx4 v[200:201], off
	v_lshl_add_u64 v[200:201], s[8:9], 0, v[160:161]
	s_add_i32 m0, s41, 0xe000
	s_nop 0
	global_load_lds_dwordx4 v[200:201], off
	s_waitcnt lgkmcnt(8)
	s_barrier
	s_waitcnt lgkmcnt(0)
	s_setprio 1
	s_waitcnt lgkmcnt(0)
	v_mfma_f32_16x16x32_bf16 v[126:129], v[130:133], v[162:165], v[126:129]
	v_mfma_f32_16x16x32_bf16 v[122:125], v[138:141], v[162:165], v[122:125]
	v_mfma_f32_16x16x32_bf16 v[118:121], v[130:133], v[176:179], v[118:121]
	v_mfma_f32_16x16x32_bf16 v[110:113], v[138:141], v[176:179], v[110:113]
	v_mfma_f32_16x16x32_bf16 v[102:105], v[130:133], v[184:187], v[102:105]
	v_mfma_f32_16x16x32_bf16 v[94:97], v[138:141], v[184:187], v[94:97]
	v_mfma_f32_16x16x32_bf16 v[86:89], v[130:133], v[192:195], v[86:89]
	v_mfma_f32_16x16x32_bf16 v[78:81], v[138:141], v[192:195], v[78:81]
	v_mfma_f32_16x16x32_bf16 v[126:129], v[134:137], v[168:171], v[126:129]
	v_mfma_f32_16x16x32_bf16 v[122:125], v[142:145], v[168:171], v[122:125]
	v_mfma_f32_16x16x32_bf16 v[118:121], v[134:137], v[180:183], v[118:121]
	v_mfma_f32_16x16x32_bf16 v[110:113], v[142:145], v[180:183], v[110:113]
	v_mfma_f32_16x16x32_bf16 v[102:105], v[134:137], v[188:191], v[102:105]
	v_mfma_f32_16x16x32_bf16 v[94:97], v[142:145], v[188:191], v[94:97]
	v_mfma_f32_16x16x32_bf16 v[86:89], v[134:137], v[196:199], v[86:89]
	v_mfma_f32_16x16x32_bf16 v[78:81], v[142:145], v[196:199], v[78:81]
	s_setprio 0
	s_barrier
	s_add_i32 s58, 0, 0x14000
	s_add_i32 s55, s55, s40
	v_add_u32_e32 v0, s58, v173
	v_lshl_add_u64 v[216:217], s[10:11], 0, v[148:149]
	s_mov_b32 m0, s55
	ds_read_b128 v[200:203], v0
	ds_read_b128 v[204:207], v0 offset:1024
	ds_read_b128 v[208:211], v0 offset:2048
	ds_read_b128 v[212:215], v0 offset:3072
	global_load_lds_dwordx4 v[216:217], off
	v_lshl_add_u64 v[218:219], s[10:11], 0, v[152:153]
	s_add_i32 m0, s55, 0x2000
	s_nop 0
	global_load_lds_dwordx4 v[218:219], off
	s_barrier
	s_waitcnt lgkmcnt(0)
	s_setprio 1
	s_waitcnt lgkmcnt(0)
	v_mfma_f32_16x16x32_bf16 v[114:117], v[200:203], v[162:165], v[114:117]
	v_mfma_f32_16x16x32_bf16 v[106:109], v[208:211], v[162:165], v[106:109]
	v_mfma_f32_16x16x32_bf16 v[98:101], v[200:203], v[176:179], v[98:101]
	v_mfma_f32_16x16x32_bf16 v[90:93], v[208:211], v[176:179], v[90:93]
	v_mfma_f32_16x16x32_bf16 v[82:85], v[200:203], v[184:187], v[82:85]
	v_mfma_f32_16x16x32_bf16 v[74:77], v[208:211], v[184:187], v[74:77]
	v_mfma_f32_16x16x32_bf16 v[70:73], v[200:203], v[192:195], v[70:73]
	v_mfma_f32_16x16x32_bf16 v[66:69], v[208:211], v[192:195], v[66:69]
	v_mfma_f32_16x16x32_bf16 v[114:117], v[204:207], v[168:171], v[114:117]
	v_mfma_f32_16x16x32_bf16 v[106:109], v[212:215], v[168:171], v[106:109]
	v_mfma_f32_16x16x32_bf16 v[98:101], v[204:207], v[180:183], v[98:101]
	v_mfma_f32_16x16x32_bf16 v[90:93], v[212:215], v[180:183], v[90:93]
	v_mfma_f32_16x16x32_bf16 v[82:85], v[204:207], v[188:191], v[82:85]
	v_mfma_f32_16x16x32_bf16 v[74:77], v[212:215], v[188:191], v[74:77]
	v_mfma_f32_16x16x32_bf16 v[70:73], v[204:207], v[196:199], v[70:73]
	v_mfma_f32_16x16x32_bf16 v[66:69], v[212:215], v[196:199], v[66:69]
	s_setprio 0
	s_mov_b32 m0, s41
	v_lshl_add_u64 v[220:221], s[28:29], 0, v[146:147]
	s_barrier
	ds_read_b128 v[162:165], v175 offset:16384
	ds_read_b128 v[168:171], v175 offset:17408
	ds_read_b128 v[176:179], v175 offset:18432
	ds_read_b128 v[180:183], v175 offset:19456
	ds_read_b128 v[184:187], v175 offset:20480
	ds_read_b128 v[188:191], v175 offset:21504
	ds_read_b128 v[192:195], v175 offset:22528
	ds_read_b128 v[196:199], v175 offset:23552
	global_load_lds_dwordx4 v[220:221], off
	v_lshl_add_u64 v[222:223], s[28:29], 0, v[150:151]
	s_mov_b32 m0, s42
	s_nop 0
	global_load_lds_dwordx4 v[222:223], off
	s_barrier
	s_waitcnt lgkmcnt(0)
	s_setprio 1
	s_waitcnt lgkmcnt(0)
	v_mfma_f32_16x16x32_bf16 v[62:65], v[130:133], v[162:165], v[62:65]
	v_mfma_f32_16x16x32_bf16 v[58:61], v[138:141], v[162:165], v[58:61]
	v_mfma_f32_16x16x32_bf16 v[54:57], v[130:133], v[176:179], v[54:57]
	v_mfma_f32_16x16x32_bf16 v[46:49], v[138:141], v[176:179], v[46:49]
	v_mfma_f32_16x16x32_bf16 v[38:41], v[130:133], v[184:187], v[38:41]
	v_mfma_f32_16x16x32_bf16 v[30:33], v[138:141], v[184:187], v[30:33]
	v_mfma_f32_16x16x32_bf16 v[22:25], v[130:133], v[192:195], v[22:25]
	v_mfma_f32_16x16x32_bf16 v[14:17], v[138:141], v[192:195], v[14:17]
	v_mfma_f32_16x16x32_bf16 v[62:65], v[134:137], v[168:171], v[62:65]
	v_mfma_f32_16x16x32_bf16 v[58:61], v[142:145], v[168:171], v[58:61]
	v_mfma_f32_16x16x32_bf16 v[54:57], v[134:137], v[180:183], v[54:57]
	v_mfma_f32_16x16x32_bf16 v[46:49], v[142:145], v[180:183], v[46:49]
	v_mfma_f32_16x16x32_bf16 v[38:41], v[134:137], v[188:191], v[38:41]
	v_mfma_f32_16x16x32_bf16 v[30:33], v[142:145], v[188:191], v[30:33]
	v_mfma_f32_16x16x32_bf16 v[22:25], v[134:137], v[196:199], v[22:25]
	v_mfma_f32_16x16x32_bf16 v[14:17], v[142:145], v[196:199], v[14:17]
	s_setprio 0
	s_barrier
; #define PG8_STAGE(bufoff, gbase, voff) do { _Pragma("unroll") for (int _i = 0; _i < 2; ++_i) \
;     __builtin_amdgcn_global_load_lds((const unsigned*)((const char*)(gbase) + (voff)[_i]), (PG8_LAS unsigned*)(lds + (bufoff) + ldsw + _i * 8192), 16, 0, 0); } while (0)
; #define PG8_LDA(dst, b, h) do { _Pragma("unroll") for (int m = 0; m < 4; ++m) _Pragma("unroll") for (int k = 0; k < 2; ++k) dst[m][k] = *(const PG8_LAS bf16x8*)(lds + PG8_SA(b, h) + aoff + m * 2048 + k * 1024); } while (0)
; #define PG8_LDB(dst, b, h) do { _Pragma("unroll") for (int n = 0; n < 2; ++n) _Pragma("unroll") for (int k = 0; k < 2; ++k) dst[n][k] = *(const PG8_LAS bf16x8*)(lds + PG8_SB(b, h) + boff + n * 2048 + k * 1024); } while (0)
; #define PG8_MMA(ai, bj, At, Bt) do { __builtin_amdgcn_s_setprio(1); _Pragma("unroll") for (int m = 0; m < 4; ++m) _Pragma("unroll") for (int n = 0; n < 2; ++n) _Pragma("unroll") for (int k = 0; k < 2; ++k) \
;     acc[ai][bj][m][n] = __builtin_amdgcn_mfma_f32_16x16x32_bf16(Bt[n][k], At[m][k], acc[ai][bj][m][n], 0, 0, 0); __builtin_amdgcn_s_setprio(0); } while (0)
; #define PG8_WAIT_V(n) asm volatile("s_waitcnt vmcnt(" #n ")" ::: "memory")
; #define PG8_WAIT_L(n) asm volatile("s_waitcnt lgkmcnt(" #n ")" ::: "memory")
; #define PG8_BAR __builtin_amdgcn_s_barrier()
; #define PG8_SCHED __builtin_amdgcn_sched_barrier(0)
; template <class Epi>
; DI void gemm_phase(PG8_LAS unsigned char* lds, const Gemm g, const StaticOrder& S, const Epi& E) {
;     ...
;       PG8_STAGE(PG8_SB(0, 1), b2 + hstepB, voffB);
;       PG8_WAIT_V(6); PG8_BAR; PG8_MMA(1, 1, At, B1); PG8_BAR;
;       PG8_LDB(B0, 1, 0); PG8_SCHED; PG8_LDA(At, 1, 0); PG8_STAGE(PG8_SA(0, 1), a2 + hstepA, voffA);
;       PG8_WAIT_L(8); PG8_BAR; PG8_WAIT_L(0); PG8_MMA(0, 0, At, B0); PG8_BAR; PG8_SCHED;
;       PG8_LDB(B1, 1, 1); PG8_STAGE(PG8_SB(1, 0), b3, voffB);
;       PG8_BAR; PG8_WAIT_L(0); PG8_MMA(0, 1, At, B1); PG8_BAR;
;       PG8_LDA(At, 1, 1); PG8_STAGE(PG8_SA(1, 0), a3, voffA);
;       PG8_BAR; PG8_WAIT_L(0); PG8_MMA(1, 0, At, B0); PG8_BAR; PG8_SCHED;
;       PG8_STAGE(PG8_SB(1, 1), b3 + hstepB, voffB);
;       PG8_WAIT_V(6); PG8_BAR; PG8_MMA(1, 1, At, B1); PG8_BAR;
	s_add_u32 s56, s10, 0x10000
	s_addc_u32 s57, s11, 0
	s_add_i32 s55, s58, s40
	v_lshl_add_u64 v[130:131], s[56:57], 0, v[148:149]
	s_mov_b32 m0, s55
	s_nop 0
	global_load_lds_dwordx4 v[130:131], off
	v_lshl_add_u64 v[130:131], s[56:57], 0, v[152:153]
	s_add_i32 m0, s55, 0x2000
	s_nop 0
	global_load_lds_dwordx4 v[130:131], off
	s_waitcnt vmcnt(6)
	s_barrier
	s_setprio 1
	v_mfma_f32_16x16x32_bf16 v[50:53], v[200:203], v[162:165], v[50:53]
	v_mfma_f32_16x16x32_bf16 v[42:45], v[208:211], v[162:165], v[42:45]
	v_mfma_f32_16x16x32_bf16 v[34:37], v[200:203], v[176:179], v[34:37]
	v_mfma_f32_16x16x32_bf16 v[26:29], v[208:211], v[176:179], v[26:29]
	v_mfma_f32_16x16x32_bf16 v[18:21], v[200:203], v[184:187], v[18:21]
	v_mfma_f32_16x16x32_bf16 v[10:13], v[208:211], v[184:187], v[10:13]
	v_mfma_f32_16x16x32_bf16 v[6:9], v[200:203], v[192:195], v[6:9]
	v_mfma_f32_16x16x32_bf16 v[2:5], v[208:211], v[192:195], v[2:5]
	v_mfma_f32_16x16x32_bf16 v[50:53], v[204:207], v[168:171], v[50:53]
	v_mfma_f32_16x16x32_bf16 v[42:45], v[212:215], v[168:171], v[42:45]
	v_mfma_f32_16x16x32_bf16 v[34:37], v[204:207], v[180:183], v[34:37]
	v_mfma_f32_16x16x32_bf16 v[26:29], v[212:215], v[180:183], v[26:29]
	v_mfma_f32_16x16x32_bf16 v[18:21], v[204:207], v[188:191], v[18:21]
	v_mfma_f32_16x16x32_bf16 v[10:13], v[212:215], v[188:191], v[10:13]
	v_mfma_f32_16x16x32_bf16 v[6:9], v[204:207], v[196:199], v[6:9]
	v_mfma_f32_16x16x32_bf16 v[2:5], v[212:215], v[196:199], v[2:5]
	s_setprio 0
	s_add_i32 s55, 0, 0x18000
	v_add_u32_e32 v0, s55, v173
	s_barrier
	ds_read_b128 v[130:133], v0
	ds_read_b128 v[134:137], v0 offset:1024
	ds_read_b128 v[138:141], v0 offset:2048
	ds_read_b128 v[142:145], v0 offset:3072
	s_add_u32 s28, s28, 0x40000
	s_addc_u32 s29, s29, 0
	s_mov_b32 m0, s43
	v_lshl_add_u64 v[200:201], s[28:29], 0, v[146:147]
	ds_read_b128 v[162:165], v175 offset:32768
	ds_read_b128 v[168:171], v175 offset:33792
	ds_read_b128 v[176:179], v175 offset:34816
	ds_read_b128 v[180:183], v175 offset:35840
	ds_read_b128 v[184:187], v175 offset:36864
	ds_read_b128 v[188:191], v175 offset:37888
	ds_read_b128 v[192:195], v175 offset:38912
	ds_read_b128 v[196:199], v175 offset:39936
	global_load_lds_dwordx4 v[200:201], off
	v_lshl_add_u64 v[200:201], s[28:29], 0, v[150:151]
	s_mov_b32 m0, s44
	s_nop 0
	global_load_lds_dwordx4 v[200:201], off
	s_waitcnt lgkmcnt(8)
	s_barrier
	s_waitcnt lgkmcnt(0)
	s_setprio 1
	s_waitcnt lgkmcnt(0)
	v_mfma_f32_16x16x32_bf16 v[126:129], v[130:133], v[162:165], v[126:129]
	v_mfma_f32_16x16x32_bf16 v[122:125], v[138:141], v[162:165], v[122:125]
	v_mfma_f32_16x16x32_bf16 v[118:121], v[130:133], v[176:179], v[118:121]
	v_mfma_f32_16x16x32_bf16 v[110:113], v[138:141], v[176:179], v[110:113]
	v_mfma_f32_16x16x32_bf16 v[102:105], v[130:133], v[184:187], v[102:105]
	v_mfma_f32_16x16x32_bf16 v[94:97], v[138:141], v[184:187], v[94:97]
	v_mfma_f32_16x16x32_bf16 v[86:89], v[130:133], v[192:195], v[86:89]
	v_mfma_f32_16x16x32_bf16 v[78:81], v[138:141], v[192:195], v[78:81]
	v_mfma_f32_16x16x32_bf16 v[126:129], v[134:137], v[168:171], v[126:129]
	v_mfma_f32_16x16x32_bf16 v[122:125], v[142:145], v[168:171], v[122:125]
	v_mfma_f32_16x16x32_bf16 v[118:121], v[134:137], v[180:183], v[118:121]
	v_mfma_f32_16x16x32_bf16 v[110:113], v[142:145], v[180:183], v[110:113]
	v_mfma_f32_16x16x32_bf16 v[102:105], v[134:137], v[188:191], v[102:105]
	v_mfma_f32_16x16x32_bf16 v[94:97], v[142:145], v[188:191], v[94:97]
	v_mfma_f32_16x16x32_bf16 v[86:89], v[134:137], v[196:199], v[86:89]
	v_mfma_f32_16x16x32_bf16 v[78:81], v[142:145], v[196:199], v[78:81]
	s_setprio 0
	s_barrier
	s_add_i32 s28, 0, 0x1c000
	s_add_i32 s29, s55, s40
	v_add_u32_e32 v0, s28, v173
	v_lshl_add_u64 v[216:217], v[216:217], 0, s[64:65]
	s_mov_b32 m0, s29
	ds_read_b128 v[200:203], v0
	ds_read_b128 v[204:207], v0 offset:1024
	ds_read_b128 v[208:211], v0 offset:2048
	ds_read_b128 v[212:215], v0 offset:3072
	global_load_lds_dwordx4 v[216:217], off
	v_lshl_add_u64 v[216:217], v[218:219], 0, s[64:65]
	s_add_i32 m0, s29, 0x2000
	s_nop 0
	global_load_lds_dwordx4 v[216:217], off
	s_barrier
	s_waitcnt lgkmcnt(0)
	s_setprio 1
	s_waitcnt lgkmcnt(0)
	v_mfma_f32_16x16x32_bf16 v[114:117], v[200:203], v[162:165], v[114:117]
	v_mfma_f32_16x16x32_bf16 v[106:109], v[208:211], v[162:165], v[106:109]
	v_mfma_f32_16x16x32_bf16 v[98:101], v[200:203], v[176:179], v[98:101]
	v_mfma_f32_16x16x32_bf16 v[90:93], v[208:211], v[176:179], v[90:93]
	v_mfma_f32_16x16x32_bf16 v[82:85], v[200:203], v[184:187], v[82:85]
	v_mfma_f32_16x16x32_bf16 v[74:77], v[208:211], v[184:187], v[74:77]
	v_mfma_f32_16x16x32_bf16 v[70:73], v[200:203], v[192:195], v[70:73]
	v_mfma_f32_16x16x32_bf16 v[66:69], v[208:211], v[192:195], v[66:69]
	v_mfma_f32_16x16x32_bf16 v[114:117], v[204:207], v[168:171], v[114:117]
	v_mfma_f32_16x16x32_bf16 v[106:109], v[212:215], v[168:171], v[106:109]
	v_mfma_f32_16x16x32_bf16 v[98:101], v[204:207], v[180:183], v[98:101]
	v_mfma_f32_16x16x32_bf16 v[90:93], v[212:215], v[180:183], v[90:93]
	v_mfma_f32_16x16x32_bf16 v[82:85], v[204:207], v[188:191], v[82:85]
	v_mfma_f32_16x16x32_bf16 v[74:77], v[212:215], v[188:191], v[74:77]
	v_mfma_f32_16x16x32_bf16 v[70:73], v[204:207], v[196:199], v[70:73]
	v_mfma_f32_16x16x32_bf16 v[66:69], v[212:215], v[196:199], v[66:69]
	s_setprio 0
	s_mov_b32 m0, s45
	v_lshl_add_u64 v[216:217], v[220:221], 0, s[64:65]
	s_barrier
	ds_read_b128 v[162:165], v175 offset:49152
	ds_read_b128 v[168:171], v175 offset:50176
	ds_read_b128 v[176:179], v175 offset:51200
	ds_read_b128 v[180:183], v175 offset:52224
	ds_read_b128 v[184:187], v175 offset:53248
	ds_read_b128 v[188:191], v175 offset:54272
	ds_read_b128 v[192:195], v175 offset:55296
	ds_read_b128 v[196:199], v175 offset:56320
	global_load_lds_dwordx4 v[216:217], off
	v_lshl_add_u64 v[216:217], v[222:223], 0, s[64:65]
	s_mov_b32 m0, s46
	s_nop 0
	global_load_lds_dwordx4 v[216:217], off
	s_barrier
; #define PG8_STAGE(bufoff, gbase, voff) do { _Pragma("unroll") for (int _i = 0; _i < 2; ++_i) \
;     __builtin_amdgcn_global_load_lds((const unsigned*)((const char*)(gbase) + (voff)[_i]), (PG8_LAS unsigned*)(lds + (bufoff) + ldsw + _i * 8192), 16, 0, 0); } while (0)
; #define PG8_LDA(dst, b, h) do { _Pragma("unroll") for (int m = 0; m < 4; ++m) _Pragma("unroll") for (int k = 0; k < 2; ++k) dst[m][k] = *(const PG8_LAS bf16x8*)(lds + PG8_SA(b, h) + aoff + m * 2048 + k * 1024); } while (0)
; #define PG8_WAIT_V(n) asm volatile("s_waitcnt vmcnt(" #n ")" ::: "memory")
; #define PG8_WAIT_L(n) asm volatile("s_waitcnt lgkmcnt(" #n ")" ::: "memory")
; template <class Epi>
; DI void gemm_phase(PG8_LAS unsigned char* lds, const Gemm g, const StaticOrder& S, const Epi& E) {
;     ...
;       PG8_BAR; PG8_WAIT_L(0); PG8_MMA(0, 1, At, B1); PG8_BAR;
;       PG8_LDA(At, 1, 1); PG8_STAGE(PG8_SA(1, 0), a3, voffA);
;       PG8_BAR; PG8_WAIT_L(0); PG8_MMA(1, 0, At, B0); PG8_BAR; PG8_SCHED;
;       PG8_STAGE(PG8_SB(1, 1), b3 + hstepB, voffB);
;       PG8_WAIT_V(6); PG8_BAR; PG8_MMA(1, 1, At, B1); PG8_BAR;
;     }
;   DI void operator()(const f32x4 (&acc)[2][2][4][2], const Unit& u, int wr, int wc, int fr, int fq) const {
;     f32x4 rs[2][2];
; #pragma unroll
;     for (int bj = 0; bj < 2; ++bj) {
;       const float* rp = rstd + 256 * u.pn + 64 * wc + 32 * bj + 8 * fq;
;       rs[bj][0] = *(const f32x4*)rp; rs[bj][1] = *(const f32x4*)(rp + 4);
;     }
; #pragma unroll
;     for (int ai = 0; ai < 2; ++ai) {
;       const int vslot = 4 * u.pm + 2 * ai + wr;
;       if (vslot < 10) {
;         bf16_t* dst = big + (size_t)(SL_AV + vslot) * SLOT_ELEMS;
; #pragma unroll
;         for (int m = 0; m < 4; ++m) {
;           const int dim = 16 * m + fr;
; #pragma unroll
;           for (int bj = 0; bj < 2; ++bj) {
;             const int tgrp = 256 * u.pn + 64 * wc + 32 * bj + (fq >> 1) * 16;
;             const int b = tgrp >> 12, s = tgrp & (SEQ - 1);
;             const f32x4 a = acc[ai][bj][m][0] * rs[bj][0], c = acc[ai][bj][m][1] * rs[bj][1];
;             uint2 w0, w1;
;             w0.x = pk_bf16(a[0], a[1]); w0.y = pk_bf16(a[2], a[3]);
;             w1.x = pk_bf16(c[0], c[1]); w1.y = pk_bf16(c[2], c[3]);
;             bf16_t* gp = dst + ((size_t)(b * 64 + dim)) * SEQ + s + (fq & 1) * 4;
;             *(uint2*)gp = w0;
;             *(uint2*)(gp + 8) = w1;
	s_waitcnt lgkmcnt(0)
	s_setprio 1
	s_waitcnt lgkmcnt(0)
	v_mfma_f32_16x16x32_bf16 v[62:65], v[130:133], v[162:165], v[62:65]
	v_mfma_f32_16x16x32_bf16 v[58:61], v[138:141], v[162:165], v[58:61]
	v_mfma_f32_16x16x32_bf16 v[54:57], v[130:133], v[176:179], v[54:57]
	v_mfma_f32_16x16x32_bf16 v[46:49], v[138:141], v[176:179], v[46:49]
	v_mfma_f32_16x16x32_bf16 v[38:41], v[130:133], v[184:187], v[38:41]
	v_mfma_f32_16x16x32_bf16 v[30:33], v[138:141], v[184:187], v[30:33]
	v_mfma_f32_16x16x32_bf16 v[22:25], v[130:133], v[192:195], v[22:25]
	v_mfma_f32_16x16x32_bf16 v[14:17], v[138:141], v[192:195], v[14:17]
	v_mfma_f32_16x16x32_bf16 v[62:65], v[134:137], v[168:171], v[62:65]
	v_mfma_f32_16x16x32_bf16 v[58:61], v[142:145], v[168:171], v[58:61]
	v_mfma_f32_16x16x32_bf16 v[54:57], v[134:137], v[180:183], v[54:57]
	v_mfma_f32_16x16x32_bf16 v[46:49], v[142:145], v[180:183], v[46:49]
	v_mfma_f32_16x16x32_bf16 v[38:41], v[134:137], v[188:191], v[38:41]
	v_mfma_f32_16x16x32_bf16 v[30:33], v[142:145], v[188:191], v[30:33]
	v_mfma_f32_16x16x32_bf16 v[22:25], v[134:137], v[196:199], v[22:25]
	v_mfma_f32_16x16x32_bf16 v[14:17], v[142:145], v[196:199], v[14:17]
	s_setprio 0
	s_barrier
	s_add_u32 s10, s10, 0x10080
	s_addc_u32 s11, s11, 0
	s_add_i32 s28, s28, s40
	v_lshl_add_u64 v[130:131], s[10:11], 0, v[148:149]
	s_mov_b32 m0, s28
	s_nop 0
	global_load_lds_dwordx4 v[130:131], off
	v_lshl_add_u64 v[130:131], s[10:11], 0, v[152:153]
	s_add_i32 m0, s28, 0x2000
	s_nop 0
	global_load_lds_dwordx4 v[130:131], off
	s_waitcnt vmcnt(6)
	s_barrier
	s_setprio 1
	v_mfma_f32_16x16x32_bf16 v[50:53], v[200:203], v[162:165], v[50:53]
	v_mfma_f32_16x16x32_bf16 v[42:45], v[208:211], v[162:165], v[42:45]
	v_mfma_f32_16x16x32_bf16 v[34:37], v[200:203], v[176:179], v[34:37]
	v_mfma_f32_16x16x32_bf16 v[26:29], v[208:211], v[176:179], v[26:29]
	v_mfma_f32_16x16x32_bf16 v[18:21], v[200:203], v[184:187], v[18:21]
	v_mfma_f32_16x16x32_bf16 v[10:13], v[208:211], v[184:187], v[10:13]
	v_mfma_f32_16x16x32_bf16 v[6:9], v[200:203], v[192:195], v[6:9]
	v_mfma_f32_16x16x32_bf16 v[2:5], v[208:211], v[192:195], v[2:5]
	v_mfma_f32_16x16x32_bf16 v[50:53], v[204:207], v[168:171], v[50:53]
	v_mfma_f32_16x16x32_bf16 v[42:45], v[212:215], v[168:171], v[42:45]
	v_mfma_f32_16x16x32_bf16 v[34:37], v[204:207], v[180:183], v[34:37]
	v_mfma_f32_16x16x32_bf16 v[26:29], v[212:215], v[180:183], v[26:29]
	v_mfma_f32_16x16x32_bf16 v[18:21], v[204:207], v[188:191], v[18:21]
	v_mfma_f32_16x16x32_bf16 v[10:13], v[212:215], v[188:191], v[10:13]
	v_mfma_f32_16x16x32_bf16 v[6:9], v[204:207], v[196:199], v[6:9]
	v_mfma_f32_16x16x32_bf16 v[2:5], v[212:215], v[196:199], v[2:5]
	s_setprio 0
	s_add_i32 s54, s54, 2
	s_add_u32 s8, s8, 0x100
	s_addc_u32 s9, s9, 0
	s_add_u32 s52, s52, 0x100
	s_addc_u32 s53, s53, 0
	s_cmp_gt_u32 s54, 13
	s_barrier
	s_cbranch_scc0 .LBB0_549
	s_lshl_b32 s10, s48, 8
	s_ashr_i32 s11, s10, 31
	v_lshl_add_u64 v[134:135], s[10:11], 2, v[154:155]
	global_load_dwordx4 v[138:141], v[134:135], off offset:16
	global_load_dwordx4 v[142:145], v[134:135], off
	global_load_dwordx4 v[130:133], v[134:135], off offset:144
	s_nop 0
	global_load_dwordx4 v[134:137], v[134:135], off offset:128
	s_lshl_b32 s1, s49, 2
	s_add_i32 s8, s1, s36
	s_lshl_b32 s1, s48, 2
	s_andn2_b32 s1, s1, 63
	v_or_b32_e32 v0, s10, v174
	v_or_b32_e32 v170, s1, v172
	v_and_b32_e32 v0, 0xfd0, v0
	v_or_b32_e32 v168, 16, v170
	v_or_b32_e32 v164, 32, v170
	v_or_b32_e32 v162, 48, v170
	s_cmp_gt_i32 s8, 9
	v_ashrrev_i32_e32 v171, 31, v170
	v_lshlrev_b32_e32 v0, 1, v0
	v_and_b32_e32 v180, 16, v228
	v_lshrrev_b32_e32 v180, 1, v180
	v_add_u32_e32 v0, v0, v180
	v_ashrrev_i32_e32 v169, 31, v168
	v_ashrrev_i32_e32 v165, 31, v164
	v_ashrrev_i32_e32 v163, 31, v162
	s_cbranch_scc1 .LBB0_552
	s_ashr_i32 s9, s8, 31
	s_lshl_b64 s[10:11], s[8:9], 23
	v_lshl_add_u64 v[176:177], v[156:157], 0, s[10:11]
	s_mov_b64 s[10:11], 0xe000000
	v_lshl_add_u64 v[176:177], v[176:177], 0, s[10:11]
	v_lshlrev_b64 v[178:179], 13, v[170:171]
	v_lshl_add_u64 v[178:179], v[176:177], 0, v[178:179]
	s_waitcnt vmcnt(0)
	v_pk_mul_f32 v[128:129], v[128:129], v[144:145]
	v_pk_mul_f32 v[126:127], v[126:127], v[142:143]
	v_pk_mul_f32 v[124:125], v[124:125], v[140:141]
	v_pk_mul_f32 v[122:123], v[122:123], v[138:139]
	v_pk_mul_f32 v[116:117], v[116:117], v[136:137]
	v_pk_mul_f32 v[114:115], v[114:115], v[134:135]
	v_pk_mul_f32 v[108:109], v[108:109], v[132:133]
	v_pk_mul_f32 v[106:107], v[106:107], v[130:131]
	v_cvt_pk_bf16_f32 v126, v126, v127
	v_cvt_pk_bf16_f32 v127, v128, v129
	v_cvt_pk_bf16_f32 v122, v122, v123
	v_cvt_pk_bf16_f32 v123, v124, v125
	v_lshl_add_u64 v[124:125], v[178:179], 0, v[0:1]
	v_cvt_pk_bf16_f32 v114, v114, v115
	v_cvt_pk_bf16_f32 v115, v116, v117
	v_cvt_pk_bf16_f32 v106, v106, v107
	v_cvt_pk_bf16_f32 v107, v108, v109
	v_mov_b32_e32 v180, v126
	v_mov_b32_e32 v181, v127
	v_mov_b32_e32 v182, v122
	v_mov_b32_e32 v183, v123
	v_mov_b32_e32 v184, v114
	v_mov_b32_e32 v185, v115
	v_mov_b32_e32 v186, v106
	v_mov_b32_e32 v187, v107
	v_permlane16_swap_b32_e32 v180, v182
	v_permlane16_swap_b32_e32 v181, v183
	v_permlane16_swap_b32_e32 v184, v186
	v_permlane16_swap_b32_e32 v185, v187
	global_store_dwordx4 v[124:125], v[180:183], off
	global_store_dwordx4 v[124:125], v[184:187], off offset:64
	v_lshlrev_b64 v[106:107], 13, v[168:169]
	v_lshl_add_u64 v[106:107], v[176:177], 0, v[106:107]
	v_pk_mul_f32 v[108:109], v[120:121], v[144:145]
	v_pk_mul_f32 v[114:115], v[118:119], v[142:143]
	v_pk_mul_f32 v[100:101], v[100:101], v[136:137]
	v_pk_mul_f32 v[98:99], v[98:99], v[134:135]
	v_pk_mul_f32 v[92:93], v[92:93], v[132:133]
	v_pk_mul_f32 v[90:91], v[90:91], v[130:131]
;   DI void operator()(const f32x4 (&acc)[2][2][4][2], const Unit& u, int wr, int wc, int fr, int fq) const {
;     ...
;         for (int m = 0; m < 4; ++m) {
;           const int dim = 16 * m + fr;
; #pragma unroll
;           for (int bj = 0; bj < 2; ++bj) {
;             const int tgrp = 256 * u.pn + 64 * wc + 32 * bj + (fq >> 1) * 16;
;             const int b = tgrp >> 12, s = tgrp & (SEQ - 1);
;             const f32x4 a = acc[ai][bj][m][0] * rs[bj][0], c = acc[ai][bj][m][1] * rs[bj][1];
;             uint2 w0, w1;
;             w0.x = pk_bf16(a[0], a[1]); w0.y = pk_bf16(a[2], a[3]);
;             w1.x = pk_bf16(c[0], c[1]); w1.y = pk_bf16(c[2], c[3]);
;             bf16_t* gp = dst + ((size_t)(b * 64 + dim)) * SEQ + s + (fq & 1) * 4;
;             *(uint2*)gp = w0;
;             *(uint2*)(gp + 8) = w1;
;           }
	v_pk_mul_f32 v[112:113], v[112:113], v[140:141]
	v_pk_mul_f32 v[110:111], v[110:111], v[138:139]
	v_cvt_pk_bf16_f32 v114, v114, v115
	v_cvt_pk_bf16_f32 v115, v108, v109
	v_lshl_add_u64 v[106:107], v[106:107], 0, v[0:1]
	v_cvt_pk_bf16_f32 v98, v98, v99
	v_cvt_pk_bf16_f32 v99, v100, v101
	v_cvt_pk_bf16_f32 v90, v90, v91
	v_cvt_pk_bf16_f32 v91, v92, v93
	v_cvt_pk_bf16_f32 v108, v110, v111
	v_cvt_pk_bf16_f32 v109, v112, v113
	v_mov_b32_e32 v180, v114
	v_mov_b32_e32 v181, v115
	v_mov_b32_e32 v182, v108
	v_mov_b32_e32 v183, v109
	v_mov_b32_e32 v184, v98
	v_mov_b32_e32 v185, v99
	v_mov_b32_e32 v186, v90
	v_mov_b32_e32 v187, v91
	v_permlane16_swap_b32_e32 v180, v182
	v_permlane16_swap_b32_e32 v181, v183
	v_permlane16_swap_b32_e32 v184, v186
	v_permlane16_swap_b32_e32 v185, v187
	global_store_dwordx4 v[106:107], v[180:183], off
	global_store_dwordx4 v[106:107], v[184:187], off offset:64
	v_lshlrev_b64 v[90:91], 13, v[164:165]
	v_lshl_add_u64 v[90:91], v[176:177], 0, v[90:91]
	v_pk_mul_f32 v[92:93], v[104:105], v[144:145]
	v_pk_mul_f32 v[98:99], v[102:103], v[142:143]
	v_pk_mul_f32 v[84:85], v[84:85], v[136:137]
	v_pk_mul_f32 v[82:83], v[82:83], v[134:135]
	v_pk_mul_f32 v[76:77], v[76:77], v[132:133]
	v_pk_mul_f32 v[74:75], v[74:75], v[130:131]
	v_pk_mul_f32 v[96:97], v[96:97], v[140:141]
	v_pk_mul_f32 v[94:95], v[94:95], v[138:139]
	v_cvt_pk_bf16_f32 v98, v98, v99
	v_cvt_pk_bf16_f32 v99, v92, v93
	v_lshl_add_u64 v[90:91], v[90:91], 0, v[0:1]
	v_cvt_pk_bf16_f32 v82, v82, v83
	v_cvt_pk_bf16_f32 v83, v84, v85
	v_cvt_pk_bf16_f32 v74, v74, v75
	v_cvt_pk_bf16_f32 v75, v76, v77
	v_cvt_pk_bf16_f32 v92, v94, v95
	v_cvt_pk_bf16_f32 v93, v96, v97
	v_mov_b32_e32 v180, v98
	v_mov_b32_e32 v181, v99
	v_mov_b32_e32 v182, v92
	v_mov_b32_e32 v183, v93
	v_mov_b32_e32 v184, v82
	v_mov_b32_e32 v185, v83
	v_mov_b32_e32 v186, v74
	v_mov_b32_e32 v187, v75
	v_permlane16_swap_b32_e32 v180, v182
	v_permlane16_swap_b32_e32 v181, v183
	v_permlane16_swap_b32_e32 v184, v186
	v_permlane16_swap_b32_e32 v185, v187
	global_store_dwordx4 v[90:91], v[180:183], off
	global_store_dwordx4 v[90:91], v[184:187], off offset:64
	v_lshlrev_b64 v[74:75], 13, v[162:163]
	v_lshl_add_u64 v[74:75], v[176:177], 0, v[74:75]
	v_pk_mul_f32 v[76:77], v[88:89], v[144:145]
	v_pk_mul_f32 v[82:83], v[86:87], v[142:143]
	v_pk_mul_f32 v[72:73], v[72:73], v[136:137]
	v_pk_mul_f32 v[70:71], v[70:71], v[134:135]
	v_pk_mul_f32 v[80:81], v[80:81], v[140:141]
	v_pk_mul_f32 v[78:79], v[78:79], v[138:139]
	v_cvt_pk_bf16_f32 v82, v82, v83
	v_cvt_pk_bf16_f32 v83, v76, v77
	v_lshl_add_u64 v[74:75], v[74:75], 0, v[0:1]
	v_pk_mul_f32 v[68:69], v[68:69], v[132:133]
	v_pk_mul_f32 v[66:67], v[66:67], v[130:131]
	v_cvt_pk_bf16_f32 v70, v70, v71
	v_cvt_pk_bf16_f32 v71, v72, v73
	v_cvt_pk_bf16_f32 v76, v78, v79
	v_cvt_pk_bf16_f32 v77, v80, v81
	v_cvt_pk_bf16_f32 v66, v66, v67
	v_cvt_pk_bf16_f32 v67, v68, v69
	v_mov_b32_e32 v180, v82
	v_mov_b32_e32 v181, v83
	v_mov_b32_e32 v182, v76
	v_mov_b32_e32 v183, v77
	v_mov_b32_e32 v184, v70
	v_mov_b32_e32 v185, v71
	v_mov_b32_e32 v186, v66
	v_mov_b32_e32 v187, v67
	v_permlane16_swap_b32_e32 v180, v182
	v_permlane16_swap_b32_e32 v181, v183
	v_permlane16_swap_b32_e32 v184, v186
	v_permlane16_swap_b32_e32 v185, v187
	global_store_dwordx4 v[74:75], v[180:183], off
	global_store_dwordx4 v[74:75], v[184:187], off offset:64
;   DI void operator()(const f32x4 (&acc)[2][2][4][2], const Unit& u, int wr, int wc, int fr, int fq) const {
;     ...
;     for (int ai = 0; ai < 2; ++ai) {
;       const int vslot = 4 * u.pm + 2 * ai + wr;
;       if (vslot < 10) {
;         bf16_t* dst = big + (size_t)(SL_AV + vslot) * SLOT_ELEMS;
; #pragma unroll
;         for (int m = 0; m < 4; ++m) {
;           const int dim = 16 * m + fr;
; #pragma unroll
;           for (int bj = 0; bj < 2; ++bj) {
;             const int tgrp = 256 * u.pn + 64 * wc + 32 * bj + (fq >> 1) * 16;
;             const int b = tgrp >> 12, s = tgrp & (SEQ - 1);
;             const f32x4 a = acc[ai][bj][m][0] * rs[bj][0], c = acc[ai][bj][m][1] * rs[bj][1];
;             uint2 w0, w1;
;             w0.x = pk_bf16(a[0], a[1]); w0.y = pk_bf16(a[2], a[3]);
;             w1.x = pk_bf16(c[0], c[1]); w1.y = pk_bf16(c[2], c[3]);
;             bf16_t* gp = dst + ((size_t)(b * 64 + dim)) * SEQ + s + (fq & 1) * 4;
;             *(uint2*)gp = w0;
;             *(uint2*)(gp + 8) = w1;
;           }
.LBB0_552:
	s_add_i32 s1, s8, 2
	v_readlane_b32 s64, v254, 56
	s_cmp_gt_i32 s1, 9
	v_readlane_b32 s65, v254, 57
	s_mov_b32 s54, 0xc2ce8ed0
	s_mov_b32 s55, 0x42b17218
	s_mov_b32 s52, 0x3fb8aa3b
	s_cbranch_scc1 .LBB0_545
	s_add_i32 s8, s8, 30
	s_ashr_i32 s9, s8, 31
	s_lshl_b64 s[8:9], s[8:9], 23
	v_lshl_add_u64 v[66:67], v[156:157], 0, s[8:9]
	v_lshlrev_b64 v[68:69], 13, v[170:171]
	v_lshl_add_u64 v[68:69], v[66:67], 0, v[68:69]
	s_waitcnt vmcnt(0)
	v_pk_mul_f32 v[64:65], v[64:65], v[144:145]
	v_pk_mul_f32 v[62:63], v[62:63], v[142:143]
	v_pk_mul_f32 v[60:61], v[60:61], v[140:141]
	v_pk_mul_f32 v[58:59], v[58:59], v[138:139]
	v_pk_mul_f32 v[52:53], v[52:53], v[136:137]
	v_pk_mul_f32 v[50:51], v[50:51], v[134:135]
	v_pk_mul_f32 v[44:45], v[44:45], v[132:133]
	v_pk_mul_f32 v[42:43], v[42:43], v[130:131]
	v_cvt_pk_bf16_f32 v62, v62, v63
	v_cvt_pk_bf16_f32 v63, v64, v65
	v_cvt_pk_bf16_f32 v58, v58, v59
	v_cvt_pk_bf16_f32 v59, v60, v61
	v_lshl_add_u64 v[60:61], v[68:69], 0, v[0:1]
	v_cvt_pk_bf16_f32 v50, v50, v51
	v_cvt_pk_bf16_f32 v51, v52, v53
	v_cvt_pk_bf16_f32 v42, v42, v43
	v_cvt_pk_bf16_f32 v43, v44, v45
	v_mov_b32_e32 v180, v62
	v_mov_b32_e32 v181, v63
	v_mov_b32_e32 v182, v58
	v_mov_b32_e32 v183, v59
	v_mov_b32_e32 v184, v50
	v_mov_b32_e32 v185, v51
	v_mov_b32_e32 v186, v42
	v_mov_b32_e32 v187, v43
	v_permlane16_swap_b32_e32 v180, v182
	v_permlane16_swap_b32_e32 v181, v183
	v_permlane16_swap_b32_e32 v184, v186
	v_permlane16_swap_b32_e32 v185, v187
	global_store_dwordx4 v[60:61], v[180:183], off
	global_store_dwordx4 v[60:61], v[184:187], off offset:64
	v_lshlrev_b64 v[42:43], 13, v[168:169]
	v_lshl_add_u64 v[42:43], v[66:67], 0, v[42:43]
	v_pk_mul_f32 v[44:45], v[56:57], v[144:145]
	v_pk_mul_f32 v[50:51], v[54:55], v[142:143]
	v_pk_mul_f32 v[36:37], v[36:37], v[136:137]
	v_pk_mul_f32 v[34:35], v[34:35], v[134:135]
	v_pk_mul_f32 v[28:29], v[28:29], v[132:133]
	v_pk_mul_f32 v[26:27], v[26:27], v[130:131]
	v_pk_mul_f32 v[48:49], v[48:49], v[140:141]
	v_pk_mul_f32 v[46:47], v[46:47], v[138:139]
	v_cvt_pk_bf16_f32 v50, v50, v51
	v_cvt_pk_bf16_f32 v51, v44, v45
	v_lshl_add_u64 v[42:43], v[42:43], 0, v[0:1]
	v_cvt_pk_bf16_f32 v34, v34, v35
	v_cvt_pk_bf16_f32 v35, v36, v37
	v_cvt_pk_bf16_f32 v26, v26, v27
	v_cvt_pk_bf16_f32 v27, v28, v29
	v_cvt_pk_bf16_f32 v44, v46, v47
	v_cvt_pk_bf16_f32 v45, v48, v49
	v_mov_b32_e32 v180, v50
	v_mov_b32_e32 v181, v51
	v_mov_b32_e32 v182, v44
	v_mov_b32_e32 v183, v45
	v_mov_b32_e32 v184, v34
	v_mov_b32_e32 v185, v35
	v_mov_b32_e32 v186, v26
	v_mov_b32_e32 v187, v27
	v_permlane16_swap_b32_e32 v180, v182
	v_permlane16_swap_b32_e32 v181, v183
	v_permlane16_swap_b32_e32 v184, v186
	v_permlane16_swap_b32_e32 v185, v187
	global_store_dwordx4 v[42:43], v[180:183], off
	global_store_dwordx4 v[42:43], v[184:187], off offset:64
	v_lshlrev_b64 v[26:27], 13, v[164:165]
	v_lshl_add_u64 v[26:27], v[66:67], 0, v[26:27]
	v_pk_mul_f32 v[28:29], v[40:41], v[144:145]
	v_pk_mul_f32 v[34:35], v[38:39], v[142:143]
	v_pk_mul_f32 v[20:21], v[20:21], v[136:137]
	v_pk_mul_f32 v[18:19], v[18:19], v[134:135]
	v_pk_mul_f32 v[12:13], v[12:13], v[132:133]
	v_pk_mul_f32 v[10:11], v[10:11], v[130:131]
	v_pk_mul_f32 v[32:33], v[32:33], v[140:141]
	v_pk_mul_f32 v[30:31], v[30:31], v[138:139]
	v_cvt_pk_bf16_f32 v34, v34, v35
	v_cvt_pk_bf16_f32 v35, v28, v29
	v_lshl_add_u64 v[26:27], v[26:27], 0, v[0:1]
	v_cvt_pk_bf16_f32 v18, v18, v19
	v_cvt_pk_bf16_f32 v19, v20, v21
	v_cvt_pk_bf16_f32 v10, v10, v11
	v_cvt_pk_bf16_f32 v11, v12, v13
	v_cvt_pk_bf16_f32 v28, v30, v31
	v_cvt_pk_bf16_f32 v29, v32, v33
	v_mov_b32_e32 v180, v34
	v_mov_b32_e32 v181, v35
	v_mov_b32_e32 v182, v28
	v_mov_b32_e32 v183, v29
	v_mov_b32_e32 v184, v18
	v_mov_b32_e32 v185, v19
	v_mov_b32_e32 v186, v10
	v_mov_b32_e32 v187, v11
	v_permlane16_swap_b32_e32 v180, v182
	v_permlane16_swap_b32_e32 v181, v183
	v_permlane16_swap_b32_e32 v184, v186
	v_permlane16_swap_b32_e32 v185, v187
	global_store_dwordx4 v[26:27], v[180:183], off
	global_store_dwordx4 v[26:27], v[184:187], off offset:64
	v_lshlrev_b64 v[10:11], 13, v[162:163]
	v_lshl_add_u64 v[10:11], v[66:67], 0, v[10:11]
	v_pk_mul_f32 v[12:13], v[24:25], v[144:145]
	v_pk_mul_f32 v[18:19], v[22:23], v[142:143]
	v_pk_mul_f32 v[8:9], v[8:9], v[136:137]
	v_pk_mul_f32 v[6:7], v[6:7], v[134:135]
	v_pk_mul_f32 v[16:17], v[16:17], v[140:141]
	v_pk_mul_f32 v[14:15], v[14:15], v[138:139]
	v_cvt_pk_bf16_f32 v18, v18, v19
	v_cvt_pk_bf16_f32 v19, v12, v13
	v_lshl_add_u64 v[10:11], v[10:11], 0, v[0:1]
	v_pk_mul_f32 v[4:5], v[4:5], v[132:133]
	v_pk_mul_f32 v[2:3], v[2:3], v[130:131]
	v_cvt_pk_bf16_f32 v6, v6, v7
	v_cvt_pk_bf16_f32 v7, v8, v9
	v_cvt_pk_bf16_f32 v12, v14, v15
	v_cvt_pk_bf16_f32 v13, v16, v17
	v_cvt_pk_bf16_f32 v2, v2, v3
	v_cvt_pk_bf16_f32 v3, v4, v5
	v_mov_b32_e32 v180, v18
	v_mov_b32_e32 v181, v19
	v_mov_b32_e32 v182, v12
	v_mov_b32_e32 v183, v13
	v_mov_b32_e32 v184, v6
	v_mov_b32_e32 v185, v7
	v_mov_b32_e32 v186, v2
	v_mov_b32_e32 v187, v3
	v_permlane16_swap_b32_e32 v180, v182
	v_permlane16_swap_b32_e32 v181, v183
	v_permlane16_swap_b32_e32 v184, v186
	v_permlane16_swap_b32_e32 v185, v187
	global_store_dwordx4 v[10:11], v[180:183], off
	global_store_dwordx4 v[10:11], v[184:187], off offset:64
	s_branch .LBB0_545
